# P10 FFN2-down as 256 units of 160 rows (balanced across CUs), skip unused A rows
# speedup vs baseline: 1.0135x; 1.0135x over previous
.LBB0_1044:
	s_cmp_lt_i32 s30, 11
	s_cselect_b64 s[4:5], -1, 0
	s_and_b64 s[6:7], s[4:5], s[0:1]
	s_andn2_b64 vcc, exec, s[6:7]
	s_cbranch_vccnz .LBB0_1065
	s_cmpk_gt_i32 s2, 0xff
	v_readfirstlane_b32 s0, v0
	s_cbranch_scc1 .LBB0_1065
	s_add_u32 s26, s28, 0x1d80000
	s_addc_u32 s27, s29, 0
	s_ashr_i32 s49, s2, 31
	s_lshr_b32 s4, s49, 29
	v_bfe_u32 v3, v0, 2, 4
	v_lshrrev_b32_e32 v4, 3, v0
	s_add_i32 s4, s2, s4
	v_and_or_b32 v5, v4, 48, v3
	v_or_b32_e32 v4, 64, v4
	s_movk_i32 s1, 0x70
	s_lshr_b32 s5, s0, 6
	s_ashr_i32 s8, s4, 3
	s_and_b32 s4, s4, -8
	v_and_or_b32 v3, v4, s1, v3
	s_lshr_b32 s1, s0, 8
	s_lshl_b32 s48, s5, 10
	s_sub_i32 s4, s2, s4
	s_cmp_lt_i32 s4, 0
	s_cselect_b32 s9, 33, 32
	s_mul_i32 s4, s4, s9
	s_add_i32 s4, s4, s8
	s_ashr_i32 s8, s4, 31
	s_lshr_b32 s8, s8, 27
	s_add_i32 s8, s4, s8
	s_ashr_i32 s9, s8, 5
	s_and_b32 s8, s8, 0xffe0
	s_sub_i32 s8, s4, s8
	s_bfe_i32 s4, s8, 0x80000
	s_bfe_u32 s4, s4, 0x3000c
	s_add_i32 s10, s8, s4
	s_bfe_i32 s4, s10, 0x80000
	s_and_b32 s10, s10, 0xf8
	s_sub_i32 s8, s8, s10
	s_lshl_b32 s9, s9, 3
	s_sext_i32_i16 s11, s4
	s_sext_i32_i8 s8, s8
	s_add_i32 s66, s9, s8
	s_ashr_i32 s8, s11, 3
	v_lshlrev_b32_e32 v1, 4, v0
	v_and_b32_e32 v2, 32, v0
	s_lshr_b32 s4, s11, 3
	s_mul_hi_i32 s9, s8, 0x160000
	s_mul_i32 s8, s8, 0x160000
	v_bitop3_b32 v1, v1, v2, 48 bitop3:0x6c
	v_and_b32_e32 v10, 64, v0
	s_add_u32 s44, s26, s8
	v_or_b32_e32 v2, v1, v10
	v_mul_u32_u24_e32 v11, 0x1600, v5
	s_addc_u32 s45, s27, s9
	s_add_i32 s50, s48, 0
	v_or_b32_e32 v128, v11, v2
	s_add_i32 m0, s50, 0x10000
	v_mul_u32_u24_e32 v12, 0x1600, v3
	global_load_lds_dwordx4 v128, s[44:45]
	s_add_i32 m0, s50, 0x12000
	v_or_b32_e32 v130, v12, v2
	s_add_u32 s8, s44, 0xb0000
	global_load_lds_dwordx4 v130, s[44:45]
	s_addc_u32 s9, s45, 0
	s_add_i32 m0, s50, 0x14000
	s_mul_i32 s12, s66, 0xdc000
	global_load_lds_dwordx4 v128, s[8:9]
	s_add_i32 m0, s50, 0x16000
	s_mul_hi_i32 s10, s66, 0xdc000
	s_add_u32 s36, s40, s12
	s_addc_u32 s37, s41, s10
	s_sub_u32 s36, s36, 0x42000
	s_subb_u32 s37, s37, 0
	s_add_i32 s51, s50, 0x2000
	global_load_lds_dwordx4 v130, s[8:9]
	s_mov_b32 m0, s50
	s_add_u32 s8, s36, 0x6e000
	global_load_lds_dwordx4 v128, s[36:37]
	s_mov_b32 m0, s51
	s_addc_u32 s9, s37, 0
	s_add_i32 s52, s50, 0x4000
	global_load_lds_dwordx4 v130, s[36:37]
	s_mov_b32 m0, s52
	s_add_i32 s53, s50, 0x6000
	global_load_lds_dwordx4 v128, s[8:9]
	s_mov_b32 m0, s53
	v_mov_b32_e32 v129, 0
	global_load_lds_dwordx4 v130, s[8:9]
	v_mov_b32_e32 v131, v129
	s_cmp_eq_u32 s1, 1
	s_mov_b32 s54, 0
	v_lshl_add_u64 v[8:9], s[44:45], 0, v[128:129]
	v_lshl_add_u64 v[6:7], s[44:45], 0, v[130:131]
	v_lshl_add_u64 v[2:3], s[36:37], 0, v[128:129]
	s_cselect_b64 s[8:9], -1, 0
	s_cmp_lg_u32 s1, 1
	v_lshl_add_u64 v[4:5], s[36:37], 0, v[130:131]
	s_cbranch_scc1 .LBB0_1048
	s_barrier
.LBB0_1048:
	s_lshl_b32 s5, s5, 5
	s_mov_b64 s[10:11], 0x80
	s_and_b32 s5, s5, 0x60
	s_add_i32 m0, s50, 0x18000
	v_lshl_add_u64 v[8:9], v[8:9], 0, s[10:11]
	s_ashr_i32 s55, s3, 31
	s_lshl_b32 s14, s1, 13
	s_lshl_b32 s15, s5, 7
	s_waitcnt vmcnt(2)
	s_barrier
	global_load_lds_dwordx4 v[8:9], off
	v_lshl_add_u64 v[6:7], v[6:7], 0, s[10:11]
	s_add_i32 m0, s50, 0x1a000
	s_add_i32 s56, s50, 0x8000
	s_add_i32 s57, s50, 0xa000
	global_load_lds_dwordx4 v[6:7], off
	v_lshl_add_u64 v[2:3], v[2:3], 0, s[10:11]
	s_mov_b32 m0, s56
	s_add_u32 s12, s44, 0xb0080
	global_load_lds_dwordx4 v[2:3], off
	v_lshl_add_u64 v[2:3], v[4:5], 0, s[10:11]
	s_mov_b32 m0, s57
	s_addc_u32 s13, s45, 0
	global_load_lds_dwordx4 v[2:3], off
	s_add_i32 m0, s50, 0x1c000
	v_lshl_add_u64 v[2:3], s[12:13], 0, v[128:129]
	global_load_lds_dwordx4 v[2:3], off
	v_lshl_add_u64 v[2:3], s[12:13], 0, v[130:131]
	s_add_i32 m0, s50, 0x1e000
	s_sext_i32_i8 s67, s4
	global_load_lds_dwordx4 v[2:3], off
	v_lshrrev_b32_e32 v3, 1, v0
	v_and_b32_e32 v3, 24, v3
	v_and_b32_e32 v2, 15, v0
	v_lshlrev_b32_e32 v4, 1, v3
	v_lshlrev_b32_e32 v5, 6, v0
	s_movk_i32 s4, 0x3c0
	v_lshlrev_b32_e32 v0, 2, v0
	v_and_or_b32 v5, v5, s4, v4
	v_and_b32_e32 v0, 32, v0
	v_mad_u32_u24 v140, s1, 48, v2
	v_lshl_or_b32 v2, v2, 6, v4
	s_waitcnt vmcnt(6)
	s_cmpk_lt_u32 s0, 0x100
	v_bitop3_b32 v2, v2, s14, v0 bitop3:0xde
	v_bitop3_b32 v141, s15, v5, v0 bitop3:0xf6
	s_cselect_b64 s[12:13], -1, 0
	s_add_i32 s58, 0, 0x10000
	s_add_i32 s59, 0, 0x14000
	v_or_b32_e32 v142, s5, v3
	v_add3_u32 v132, v11, v1, v10
	v_mov_b32_e32 v133, v129
	v_add3_u32 v134, v12, v1, v10
	v_mov_b32_e32 v135, v129
	v_mov_b64_e32 v[136:137], 0x100
	v_mov_b64_e32 v[138:139], 0xff
	v_add_u32_e32 v143, s58, v141
	v_add_u32_e32 v144, s59, v141
	s_cmp_lt_u32 s48, 0x1800
	s_cselect_b64 s[100:101], 1, -1
	s_movk_i32 s98, 0x1800
	s_cmp_eq_u32 s1, 1
	s_cselect_b32 s98, 0x1000, s98
	v_add_u32_e32 v145, s98, v2
	s_mov_b64 s[14:15], 0x40000
	s_mov_b32 s60, 0x40000
	s_mov_b64 s[18:19], 0x48000
	s_mov_b32 s61, 0x48000
	s_mov_b64 s[20:21], 0x50000
	s_mov_b32 s62, 0x50000
	s_mov_b64 s[22:23], 0x58000
	s_mov_b32 s63, 0x58000
	s_barrier
	s_waitcnt vmcnt(0)
	s_branch .LBB0_1051

.LBB0_1051:
	s_add_i32 s54, s54, 1
	s_mul_i32 s0, s54, s55
	s_mul_hi_u32 s1, s54, s3
	s_add_i32 s1, s1, s0
	s_mul_i32 s0, s54, s3
	s_add_u32 s4, s0, s2
	s_addc_u32 s5, s1, s49
	v_cmp_gt_i64_e32 vcc, s[4:5], v[138:139]
	v_cmp_lt_i64_e64 s[0:1], s[4:5], v[136:137]
	s_cbranch_vccnz .LBB0_1053
	s_ashr_i32 s5, s4, 31
	s_lshr_b32 s5, s5, 29
	s_add_i32 s5, s4, s5
	s_ashr_i32 s24, s5, 3
	s_and_b32 s5, s5, -8
	s_sub_i32 s4, s4, s5
	s_cmp_lt_i32 s4, 0
	s_cselect_b32 s5, 33, 32
	s_mul_i32 s4, s4, s5
	s_add_i32 s4, s4, s24
	s_ashr_i32 s5, s4, 31
	s_lshr_b32 s5, s5, 27
	s_add_i32 s5, s4, s5
	s_ashr_i32 s24, s5, 5
	s_lshl_b32 s24, s24, 3
	s_sub_i32 s25, 64, s24
	s_min_i32 s25, s25, 8
	s_abs_i32 s46, s25
	v_cvt_f32_u32_e32 v0, s46
	s_sub_i32 s64, 0, s46
	s_andn2_b32 s5, s5, 31
	s_sub_i32 s4, s4, s5
	v_rcp_iflag_f32_e32 v0, v0
	s_abs_i32 s5, s4
	s_xor_b32 s47, s4, s25
	s_ashr_i32 s47, s47, 31
	v_mul_f32_e32 v0, 0x4f7ffffe, v0
	v_cvt_u32_f32_e32 v0, v0
	s_nop 0
	v_readfirstlane_b32 s65, v0
	s_mul_i32 s64, s64, s65
	s_mul_hi_u32 s64, s65, s64
	s_add_i32 s65, s65, s64
	s_mul_hi_u32 s64, s5, s65
	s_mul_i32 s65, s64, s46
	s_sub_i32 s5, s5, s65
	s_add_i32 s68, s64, 1
	s_sub_i32 s65, s5, s46
	s_cmp_ge_u32 s5, s46
	s_cselect_b32 s64, s68, s64
	s_cselect_b32 s5, s65, s5
	s_add_i32 s65, s64, 1
	s_cmp_ge_u32 s5, s46
	s_cselect_b32 s5, s65, s64
	s_xor_b32 s5, s5, s47
	s_sub_i32 s64, s5, s47
	s_mul_i32 s5, s64, s25
	s_sub_i32 s4, s4, s5
	s_add_i32 s65, s24, s4
.LBB0_1053:
	s_nop 0
	v_cndmask_b32_e64 v0, 0, 1, s[0:1]
	v_cmp_ne_u32_e64 s[4:5], 1, v0
	s_andn2_b64 vcc, exec, s[0:1]
	s_mov_b64 s[0:1], s[36:37]
	s_cbranch_vccnz .LBB0_1055
	s_mul_i32 s0, s65, 0xdc000
	s_mul_hi_i32 s1, s65, 0xdc000
	s_add_u32 s0, s40, s0
	s_addc_u32 s1, s41, s1
	s_sub_u32 s0, s0, 0x42000
	s_subb_u32 s1, s1, 0

.LBB0_1057:
	s_add_u32 s36, s36, 0x6e080
	s_addc_u32 s37, s37, 0
	s_add_u32 s68, s44, 0x100
	v_mov_b32_e32 v0, 0
	s_addc_u32 s69, s45, 0
	s_mov_b32 s70, -2
	v_mov_b32_e32 v1, v0
	v_mov_b32_e32 v2, v0
	v_mov_b32_e32 v3, v0
	v_mov_b32_e32 v4, v0
	v_mov_b32_e32 v5, v0
	v_mov_b32_e32 v6, v0
	v_mov_b32_e32 v7, v0
	v_mov_b32_e32 v8, v0
	v_mov_b32_e32 v9, v0
	v_mov_b32_e32 v10, v0
	v_mov_b32_e32 v11, v0
	v_mov_b32_e32 v12, v0
	v_mov_b32_e32 v13, v0
	v_mov_b32_e32 v14, v0
	v_mov_b32_e32 v15, v0
	v_mov_b32_e32 v24, v0
	v_mov_b32_e32 v25, v0
	v_mov_b32_e32 v26, v0
	v_mov_b32_e32 v27, v0
	v_mov_b32_e32 v28, v0
	v_mov_b32_e32 v29, v0
	v_mov_b32_e32 v30, v0
	v_mov_b32_e32 v31, v0
	v_mov_b32_e32 v40, v0
	v_mov_b32_e32 v41, v0
	v_mov_b32_e32 v42, v0
	v_mov_b32_e32 v43, v0
	v_mov_b32_e32 v44, v0
	v_mov_b32_e32 v45, v0
	v_mov_b32_e32 v46, v0
	v_mov_b32_e32 v47, v0
	v_mov_b32_e32 v16, v0
	v_mov_b32_e32 v17, v0
	v_mov_b32_e32 v18, v0
	v_mov_b32_e32 v19, v0
	v_mov_b32_e32 v20, v0
	v_mov_b32_e32 v21, v0
	v_mov_b32_e32 v22, v0
	v_mov_b32_e32 v23, v0
	v_mov_b32_e32 v32, v0
	v_mov_b32_e32 v33, v0
	v_mov_b32_e32 v34, v0
	v_mov_b32_e32 v35, v0
	v_mov_b32_e32 v36, v0
	v_mov_b32_e32 v37, v0
	v_mov_b32_e32 v38, v0
	v_mov_b32_e32 v39, v0
	v_mov_b32_e32 v48, v0
	v_mov_b32_e32 v49, v0
	v_mov_b32_e32 v50, v0
	v_mov_b32_e32 v51, v0
	v_mov_b32_e32 v52, v0
	v_mov_b32_e32 v53, v0
	v_mov_b32_e32 v54, v0
	v_mov_b32_e32 v55, v0
	v_mov_b32_e32 v56, v0
	v_mov_b32_e32 v57, v0
	v_mov_b32_e32 v58, v0
	v_mov_b32_e32 v59, v0
	v_mov_b32_e32 v60, v0
	v_mov_b32_e32 v61, v0
	v_mov_b32_e32 v62, v0
	v_mov_b32_e32 v63, v0
	v_mov_b32_e32 v64, v0
	v_mov_b32_e32 v65, v0
	v_mov_b32_e32 v66, v0
	v_mov_b32_e32 v67, v0
	v_mov_b32_e32 v68, v0
	v_mov_b32_e32 v69, v0
	v_mov_b32_e32 v70, v0
	v_mov_b32_e32 v71, v0
	v_mov_b32_e32 v72, v0
	v_mov_b32_e32 v73, v0
	v_mov_b32_e32 v74, v0
	v_mov_b32_e32 v75, v0
	v_mov_b32_e32 v76, v0
	v_mov_b32_e32 v77, v0
	v_mov_b32_e32 v78, v0
	v_mov_b32_e32 v79, v0
	v_mov_b32_e32 v88, v0
	v_mov_b32_e32 v89, v0
	v_mov_b32_e32 v90, v0
	v_mov_b32_e32 v91, v0
	v_mov_b32_e32 v92, v0
	v_mov_b32_e32 v93, v0
	v_mov_b32_e32 v94, v0
	v_mov_b32_e32 v95, v0
	v_mov_b32_e32 v104, v0
	v_mov_b32_e32 v105, v0
	v_mov_b32_e32 v106, v0
	v_mov_b32_e32 v107, v0
	v_mov_b32_e32 v108, v0
	v_mov_b32_e32 v109, v0
	v_mov_b32_e32 v110, v0
	v_mov_b32_e32 v111, v0
	v_mov_b32_e32 v80, v0
	v_mov_b32_e32 v81, v0
	v_mov_b32_e32 v82, v0
	v_mov_b32_e32 v83, v0
	v_mov_b32_e32 v84, v0
	v_mov_b32_e32 v85, v0
	v_mov_b32_e32 v86, v0
	v_mov_b32_e32 v87, v0
	v_mov_b32_e32 v96, v0
	v_mov_b32_e32 v97, v0
	v_mov_b32_e32 v98, v0
	v_mov_b32_e32 v99, v0
	v_mov_b32_e32 v100, v0
	v_mov_b32_e32 v101, v0
	v_mov_b32_e32 v102, v0
	v_mov_b32_e32 v103, v0
	v_mov_b32_e32 v112, v0
	v_mov_b32_e32 v113, v0
	v_mov_b32_e32 v114, v0
	v_mov_b32_e32 v115, v0
	v_mov_b32_e32 v116, v0
	v_mov_b32_e32 v117, v0
	v_mov_b32_e32 v118, v0
	v_mov_b32_e32 v119, v0
	v_mov_b32_e32 v120, v0
	v_mov_b32_e32 v121, v0
	v_mov_b32_e32 v122, v0
	v_mov_b32_e32 v123, v0
	v_mov_b32_e32 v124, v0
	v_mov_b32_e32 v125, v0
	v_mov_b32_e32 v126, v0
	v_mov_b32_e32 v127, v0
.LBB0_1058:
	ds_read_b128 v[146:149], v143
	ds_read_b128 v[150:153], v143 offset:1024
	ds_read_b128 v[154:157], v143 offset:2048
	ds_read_b128 v[158:161], v143 offset:3072
	ds_read_b128 v[166:169], v144
	ds_read_b128 v[170:173], v144 offset:1024
	ds_read_b128 v[174:177], v144 offset:2048
	ds_read_b128 v[178:181], v144 offset:3072
	s_add_u32 s44, s36, 0xfff92080
	s_addc_u32 s45, s37, -1
	s_cmp_eq_u32 s70, 40
	s_cselect_b32 s47, s1, s45
	s_cselect_b32 s46, s0, s44
	s_cselect_b32 s45, s25, s69
	s_cselect_b32 s44, s24, s68
	v_lshl_add_u64 v[162:163], s[36:37], 0, v[132:133]
	s_add_i32 m0, s50, 0xc000
	ds_read_b128 v[182:185], v145
	ds_read_b128 v[186:189], v145 offset:1024
	ds_read_b128 v[190:193], v145 offset:2048
	ds_read_b128 v[194:197], v145 offset:3072
	ds_read_b128 v[198:201], v145 offset:4096
	ds_read_b128 v[202:205], v145 offset:5120
	s_mov_b64 exec, s[100:101]
	global_load_lds_dwordx4 v[162:163], off
	s_mov_b64 exec, -1
	v_lshl_add_u64 v[162:163], s[36:37], 0, v[134:135]
	s_add_i32 m0, s50, 0xe000
	s_nop 0
	global_load_lds_dwordx4 v[162:163], off
	s_waitcnt vmcnt(8)
	s_waitcnt lgkmcnt(0)
	s_barrier
	s_setprio 1
	s_waitcnt lgkmcnt(0)
	v_mfma_f32_16x16x32_bf16 v[124:127], v[146:149], v[182:185], v[124:127]
	v_mfma_f32_16x16x32_bf16 v[120:123], v[154:157], v[182:185], v[120:123]
	v_mfma_f32_16x16x32_bf16 v[124:127], v[150:153], v[186:189], v[124:127]
	v_mfma_f32_16x16x32_bf16 v[120:123], v[158:161], v[186:189], v[120:123]
	v_mfma_f32_16x16x32_bf16 v[108:111], v[166:169], v[182:185], v[108:111]
	v_mfma_f32_16x16x32_bf16 v[104:107], v[174:177], v[182:185], v[104:107]
	v_mfma_f32_16x16x32_bf16 v[108:111], v[170:173], v[186:189], v[108:111]
	v_mfma_f32_16x16x32_bf16 v[104:107], v[178:181], v[186:189], v[104:107]
	v_mfma_f32_16x16x32_bf16 v[116:119], v[146:149], v[190:193], v[116:119]
	v_mfma_f32_16x16x32_bf16 v[112:115], v[154:157], v[190:193], v[112:115]
	v_mfma_f32_16x16x32_bf16 v[116:119], v[150:153], v[194:197], v[116:119]
	v_mfma_f32_16x16x32_bf16 v[112:115], v[158:161], v[194:197], v[112:115]
	v_mfma_f32_16x16x32_bf16 v[92:95], v[166:169], v[190:193], v[92:95]
	v_mfma_f32_16x16x32_bf16 v[88:91], v[174:177], v[190:193], v[88:91]
	v_mfma_f32_16x16x32_bf16 v[92:95], v[170:173], v[194:197], v[92:95]
	v_mfma_f32_16x16x32_bf16 v[88:91], v[178:181], v[194:197], v[88:91]
	s_cmp_eq_u32 s12, 0
	s_cbranch_scc1 .Lp10_sk0
	v_mfma_f32_16x16x32_bf16 v[100:103], v[146:149], v[198:201], v[100:103]
	v_mfma_f32_16x16x32_bf16 v[96:99], v[154:157], v[198:201], v[96:99]
	v_mfma_f32_16x16x32_bf16 v[100:103], v[150:153], v[202:205], v[100:103]
	v_mfma_f32_16x16x32_bf16 v[96:99], v[158:161], v[202:205], v[96:99]
	v_mfma_f32_16x16x32_bf16 v[76:79], v[166:169], v[198:201], v[76:79]
	v_mfma_f32_16x16x32_bf16 v[72:75], v[174:177], v[198:201], v[72:75]
	v_mfma_f32_16x16x32_bf16 v[76:79], v[170:173], v[202:205], v[76:79]
	v_mfma_f32_16x16x32_bf16 v[72:75], v[178:181], v[202:205], v[72:75]
.Lp10_sk0:
	s_setprio 0
	s_barrier
	s_add_i32 s71, s58, s48
	v_lshl_add_u64 v[162:163], s[44:45], 0, v[128:129]
	s_mov_b32 m0, s71
	ds_read_b128 v[182:185], v145 offset:16384
	ds_read_b128 v[186:189], v145 offset:17408
	ds_read_b128 v[190:193], v145 offset:18432
	ds_read_b128 v[194:197], v145 offset:19456
	ds_read_b128 v[198:201], v145 offset:20480
	ds_read_b128 v[202:205], v145 offset:21504
	global_load_lds_dwordx4 v[162:163], off
	s_add_i32 m0, s71, 0x2000
	s_add_u32 s72, s44, 0xb0000
	v_lshl_add_u64 v[214:215], s[44:45], 0, v[130:131]
	s_addc_u32 s73, s45, 0
	s_add_i32 s71, s59, s48
	global_load_lds_dwordx4 v[214:215], off
	v_lshl_add_u64 v[216:217], s[72:73], 0, v[128:129]
	s_mov_b32 m0, s71
	v_lshl_add_u64 v[218:219], s[46:47], 0, v[130:131]
	global_load_lds_dwordx4 v[216:217], off
	v_lshl_add_u64 v[216:217], s[72:73], 0, v[130:131]
	s_add_i32 m0, s71, 0x2000
	s_nop 0
	global_load_lds_dwordx4 v[216:217], off
	v_lshl_add_u64 v[216:217], s[46:47], 0, v[128:129]
	s_mov_b32 m0, s50
	s_nop 0
	s_mov_b64 exec, s[100:101]
	global_load_lds_dwordx4 v[216:217], off
	s_mov_b64 exec, -1
	s_mov_b32 m0, s51
	s_nop 0
	global_load_lds_dwordx4 v[218:219], off
	s_waitcnt vmcnt(8)
	s_waitcnt lgkmcnt(0)
	s_barrier
	s_setprio 1
	s_waitcnt lgkmcnt(0)
	v_mfma_f32_16x16x32_bf16 v[60:63], v[146:149], v[182:185], v[60:63]
	v_mfma_f32_16x16x32_bf16 v[56:59], v[154:157], v[182:185], v[56:59]
	v_mfma_f32_16x16x32_bf16 v[60:63], v[150:153], v[186:189], v[60:63]
	v_mfma_f32_16x16x32_bf16 v[56:59], v[158:161], v[186:189], v[56:59]
	v_mfma_f32_16x16x32_bf16 v[44:47], v[166:169], v[182:185], v[44:47]
	v_mfma_f32_16x16x32_bf16 v[40:43], v[174:177], v[182:185], v[40:43]
	v_mfma_f32_16x16x32_bf16 v[44:47], v[170:173], v[186:189], v[44:47]
	v_mfma_f32_16x16x32_bf16 v[40:43], v[178:181], v[186:189], v[40:43]
	v_mfma_f32_16x16x32_bf16 v[52:55], v[146:149], v[190:193], v[52:55]
	v_mfma_f32_16x16x32_bf16 v[48:51], v[154:157], v[190:193], v[48:51]
	v_mfma_f32_16x16x32_bf16 v[52:55], v[150:153], v[194:197], v[52:55]
	v_mfma_f32_16x16x32_bf16 v[48:51], v[158:161], v[194:197], v[48:51]
	v_mfma_f32_16x16x32_bf16 v[28:31], v[166:169], v[190:193], v[28:31]
	v_mfma_f32_16x16x32_bf16 v[24:27], v[174:177], v[190:193], v[24:27]
	v_mfma_f32_16x16x32_bf16 v[28:31], v[170:173], v[194:197], v[28:31]
	v_mfma_f32_16x16x32_bf16 v[24:27], v[178:181], v[194:197], v[24:27]
	s_cmp_eq_u32 s12, 0
	s_cbranch_scc1 .Lp10_sk1
	v_mfma_f32_16x16x32_bf16 v[36:39], v[146:149], v[198:201], v[36:39]
	v_mfma_f32_16x16x32_bf16 v[32:35], v[154:157], v[198:201], v[32:35]
	v_mfma_f32_16x16x32_bf16 v[36:39], v[150:153], v[202:205], v[36:39]
	v_mfma_f32_16x16x32_bf16 v[32:35], v[158:161], v[202:205], v[32:35]
	v_mfma_f32_16x16x32_bf16 v[12:15], v[166:169], v[198:201], v[12:15]
	v_mfma_f32_16x16x32_bf16 v[8:11], v[174:177], v[198:201], v[8:11]
	v_mfma_f32_16x16x32_bf16 v[12:15], v[170:173], v[202:205], v[12:15]
	v_mfma_f32_16x16x32_bf16 v[8:11], v[178:181], v[202:205], v[8:11]
.Lp10_sk1:
	s_setprio 0
	s_barrier
	s_add_i32 s71, 0, 0x18000
	s_add_i32 s72, 0, 0x1c000
	v_add_u32_e32 v158, s71, v141
	v_add_u32_e32 v165, s72, v141
	ds_read_b128 v[146:149], v158
	ds_read_b128 v[150:153], v158 offset:1024
	ds_read_b128 v[154:157], v158 offset:2048
	ds_read_b128 v[158:161], v158 offset:3072
	ds_read_b128 v[166:169], v165
	ds_read_b128 v[170:173], v165 offset:1024
	ds_read_b128 v[174:177], v165 offset:2048
	ds_read_b128 v[178:181], v165 offset:3072
	s_add_u32 s46, s46, 0x6e000
	s_addc_u32 s47, s47, 0
	s_mov_b32 m0, s52
	v_lshl_add_u64 v[220:221], s[46:47], 0, v[128:129]
	ds_read_b128 v[182:185], v145 offset:32768
	ds_read_b128 v[186:189], v145 offset:33792
	ds_read_b128 v[190:193], v145 offset:34816
	ds_read_b128 v[194:197], v145 offset:35840
	ds_read_b128 v[198:201], v145 offset:36864
	ds_read_b128 v[202:205], v145 offset:37888
	s_mov_b64 exec, s[100:101]
	global_load_lds_dwordx4 v[220:221], off
	s_mov_b64 exec, -1
	v_lshl_add_u64 v[220:221], s[46:47], 0, v[130:131]
	s_mov_b32 m0, s53
	s_nop 0
	global_load_lds_dwordx4 v[220:221], off
	s_waitcnt vmcnt(8)
	s_waitcnt lgkmcnt(0)
	s_barrier
	s_setprio 1
	s_waitcnt lgkmcnt(0)
	v_mfma_f32_16x16x32_bf16 v[124:127], v[146:149], v[182:185], v[124:127]
	v_mfma_f32_16x16x32_bf16 v[120:123], v[154:157], v[182:185], v[120:123]
	v_mfma_f32_16x16x32_bf16 v[124:127], v[150:153], v[186:189], v[124:127]
	v_mfma_f32_16x16x32_bf16 v[120:123], v[158:161], v[186:189], v[120:123]
	v_mfma_f32_16x16x32_bf16 v[108:111], v[166:169], v[182:185], v[108:111]
	v_mfma_f32_16x16x32_bf16 v[104:107], v[174:177], v[182:185], v[104:107]
	v_mfma_f32_16x16x32_bf16 v[108:111], v[170:173], v[186:189], v[108:111]
	v_mfma_f32_16x16x32_bf16 v[104:107], v[178:181], v[186:189], v[104:107]
	v_mfma_f32_16x16x32_bf16 v[116:119], v[146:149], v[190:193], v[116:119]
	v_mfma_f32_16x16x32_bf16 v[112:115], v[154:157], v[190:193], v[112:115]
	v_mfma_f32_16x16x32_bf16 v[116:119], v[150:153], v[194:197], v[116:119]
	v_mfma_f32_16x16x32_bf16 v[112:115], v[158:161], v[194:197], v[112:115]
	v_mfma_f32_16x16x32_bf16 v[92:95], v[166:169], v[190:193], v[92:95]
	v_mfma_f32_16x16x32_bf16 v[88:91], v[174:177], v[190:193], v[88:91]
	v_mfma_f32_16x16x32_bf16 v[92:95], v[170:173], v[194:197], v[92:95]
	v_mfma_f32_16x16x32_bf16 v[88:91], v[178:181], v[194:197], v[88:91]
	s_cmp_eq_u32 s12, 0
	s_cbranch_scc1 .Lp10_sk2
	v_mfma_f32_16x16x32_bf16 v[100:103], v[146:149], v[198:201], v[100:103]
	v_mfma_f32_16x16x32_bf16 v[96:99], v[154:157], v[198:201], v[96:99]
	v_mfma_f32_16x16x32_bf16 v[100:103], v[150:153], v[202:205], v[100:103]
	v_mfma_f32_16x16x32_bf16 v[96:99], v[158:161], v[202:205], v[96:99]
	v_mfma_f32_16x16x32_bf16 v[76:79], v[166:169], v[198:201], v[76:79]
	v_mfma_f32_16x16x32_bf16 v[72:75], v[174:177], v[198:201], v[72:75]
	v_mfma_f32_16x16x32_bf16 v[76:79], v[170:173], v[202:205], v[76:79]
	v_mfma_f32_16x16x32_bf16 v[72:75], v[178:181], v[202:205], v[72:75]
.Lp10_sk2:
	s_setprio 0
	s_barrier
	s_add_i32 s46, s71, s48
	v_lshl_add_u64 v[162:163], v[162:163], 0, s[10:11]
	s_mov_b32 m0, s46
	ds_read_b128 v[182:185], v145 offset:49152
	ds_read_b128 v[186:189], v145 offset:50176
	ds_read_b128 v[190:193], v145 offset:51200
	ds_read_b128 v[194:197], v145 offset:52224
	ds_read_b128 v[198:201], v145 offset:53248
	ds_read_b128 v[202:205], v145 offset:54272
	global_load_lds_dwordx4 v[162:163], off
	s_add_i32 m0, s46, 0x2000
	s_add_u32 s44, s44, 0xb0080
	v_lshl_add_u64 v[162:163], v[214:215], 0, s[10:11]
	s_addc_u32 s45, s45, 0
	s_add_i32 s46, s72, s48
	global_load_lds_dwordx4 v[162:163], off
	v_lshl_add_u64 v[162:163], s[44:45], 0, v[128:129]
	s_mov_b32 m0, s46
	s_nop 0
	global_load_lds_dwordx4 v[162:163], off
	v_lshl_add_u64 v[162:163], s[44:45], 0, v[130:131]
	s_add_i32 m0, s46, 0x2000
	s_nop 0
	global_load_lds_dwordx4 v[162:163], off
	v_lshl_add_u64 v[162:163], v[216:217], 0, s[10:11]
	s_mov_b32 m0, s56
	s_nop 0
	s_mov_b64 exec, s[100:101]
	global_load_lds_dwordx4 v[162:163], off
	s_mov_b64 exec, -1
	v_lshl_add_u64 v[162:163], v[218:219], 0, s[10:11]
	s_mov_b32 m0, s57
	s_nop 0
	global_load_lds_dwordx4 v[162:163], off
	s_waitcnt vmcnt(8)
	s_waitcnt lgkmcnt(0)
	s_barrier
	s_setprio 1
	s_waitcnt lgkmcnt(0)
	v_mfma_f32_16x16x32_bf16 v[60:63], v[146:149], v[182:185], v[60:63]
	v_mfma_f32_16x16x32_bf16 v[56:59], v[154:157], v[182:185], v[56:59]
	v_mfma_f32_16x16x32_bf16 v[60:63], v[150:153], v[186:189], v[60:63]
	v_mfma_f32_16x16x32_bf16 v[56:59], v[158:161], v[186:189], v[56:59]
	v_mfma_f32_16x16x32_bf16 v[44:47], v[166:169], v[182:185], v[44:47]
	v_mfma_f32_16x16x32_bf16 v[40:43], v[174:177], v[182:185], v[40:43]
	v_mfma_f32_16x16x32_bf16 v[44:47], v[170:173], v[186:189], v[44:47]
	v_mfma_f32_16x16x32_bf16 v[40:43], v[178:181], v[186:189], v[40:43]
	v_mfma_f32_16x16x32_bf16 v[52:55], v[146:149], v[190:193], v[52:55]
	v_mfma_f32_16x16x32_bf16 v[48:51], v[154:157], v[190:193], v[48:51]
	v_mfma_f32_16x16x32_bf16 v[52:55], v[150:153], v[194:197], v[52:55]
	v_mfma_f32_16x16x32_bf16 v[48:51], v[158:161], v[194:197], v[48:51]
	v_mfma_f32_16x16x32_bf16 v[28:31], v[166:169], v[190:193], v[28:31]
	v_mfma_f32_16x16x32_bf16 v[24:27], v[174:177], v[190:193], v[24:27]
	v_mfma_f32_16x16x32_bf16 v[28:31], v[170:173], v[194:197], v[28:31]
	v_mfma_f32_16x16x32_bf16 v[24:27], v[178:181], v[194:197], v[24:27]
	s_cmp_eq_u32 s12, 0
	s_cbranch_scc1 .Lp10_sk3
	v_mfma_f32_16x16x32_bf16 v[36:39], v[146:149], v[198:201], v[36:39]
	v_mfma_f32_16x16x32_bf16 v[32:35], v[154:157], v[198:201], v[32:35]
	v_mfma_f32_16x16x32_bf16 v[36:39], v[150:153], v[202:205], v[36:39]
	v_mfma_f32_16x16x32_bf16 v[32:35], v[158:161], v[202:205], v[32:35]
	v_mfma_f32_16x16x32_bf16 v[12:15], v[166:169], v[198:201], v[12:15]
	v_mfma_f32_16x16x32_bf16 v[8:11], v[174:177], v[198:201], v[8:11]
	v_mfma_f32_16x16x32_bf16 v[12:15], v[170:173], v[202:205], v[12:15]
	v_mfma_f32_16x16x32_bf16 v[8:11], v[178:181], v[202:205], v[8:11]
.Lp10_sk3:
	s_setprio 0
	s_barrier
	s_add_i32 s70, s70, 2
	s_add_u32 s36, s36, 0x100
	s_addc_u32 s37, s37, 0
	s_add_u32 s68, s68, 0x100
	s_addc_u32 s69, s69, 0
	s_cmp_gt_u32 s70, 41
	s_cbranch_scc0 .LBB0_1058
	s_and_b64 vcc, exec, s[12:13]
	s_cbranch_vccz .LBB0_1061
	s_barrier
.LBB0_1061:
	s_mul_i32 s98, s66, 0xa0
	v_lshl_or_b32 v148, s67, 8, v142
	v_add_u32_e32 v146, s98, v140
	v_ashrrev_i32_e32 v149, 31, v148
	v_ashrrev_i32_e32 v147, 31, v146
	v_lshlrev_b64 v[148:149], 1, v[148:149]
	v_lshlrev_b64 v[150:151], 11, v[146:147]
	v_lshl_add_u64 v[150:151], s[42:43], 0, v[150:151]
	v_lshl_add_u64 v[150:151], v[150:151], 0, v[148:149]
	v_cvt_pk_bf16_f32 v166, v124, v125
	v_cvt_pk_bf16_f32 v167, v126, v127
	v_cvt_pk_bf16_f32 v168, v120, v121
	v_cvt_pk_bf16_f32 v169, v122, v123
	global_store_dwordx4 v[150:151], v[166:169], off
	v_cvt_pk_bf16_f32 v170, v108, v109
	v_cvt_pk_bf16_f32 v171, v110, v111
	v_cvt_pk_bf16_f32 v172, v104, v105
	v_cvt_pk_bf16_f32 v173, v106, v107
	global_store_dwordx4 v[150:151], v[170:173], off offset:256
	v_mov_b32_e32 v152, 0x8000
	v_mov_b32_e32 v153, 0
	v_lshl_add_u64 v[152:153], v[150:151], 0, v[152:153]
	v_cvt_pk_bf16_f32 v174, v116, v117
	v_cvt_pk_bf16_f32 v175, v118, v119
	v_cvt_pk_bf16_f32 v176, v112, v113
	v_cvt_pk_bf16_f32 v177, v114, v115
	global_store_dwordx4 v[152:153], v[174:177], off
	v_cvt_pk_bf16_f32 v178, v92, v93
	v_cvt_pk_bf16_f32 v179, v94, v95
	v_cvt_pk_bf16_f32 v180, v88, v89
	v_cvt_pk_bf16_f32 v181, v90, v91
	global_store_dwordx4 v[152:153], v[178:181], off offset:256
	v_mov_b32_e32 v154, 0x28000
	v_mov_b32_e32 v155, 0
	v_lshl_add_u64 v[154:155], v[150:151], 0, v[154:155]
	v_cvt_pk_bf16_f32 v182, v60, v61
	v_cvt_pk_bf16_f32 v183, v62, v63
	v_cvt_pk_bf16_f32 v184, v56, v57
	v_cvt_pk_bf16_f32 v185, v58, v59
	global_store_dwordx4 v[154:155], v[182:185], off
	v_cvt_pk_bf16_f32 v186, v44, v45
	v_cvt_pk_bf16_f32 v187, v46, v47
	v_cvt_pk_bf16_f32 v188, v40, v41
	v_cvt_pk_bf16_f32 v189, v42, v43
	global_store_dwordx4 v[154:155], v[186:189], off offset:256
	v_mov_b32_e32 v156, 0x30000
	v_mov_b32_e32 v157, 0
	v_lshl_add_u64 v[156:157], v[150:151], 0, v[156:157]
	v_cvt_pk_bf16_f32 v190, v52, v53
	v_cvt_pk_bf16_f32 v191, v54, v55
	v_cvt_pk_bf16_f32 v192, v48, v49
	v_cvt_pk_bf16_f32 v193, v50, v51
	global_store_dwordx4 v[156:157], v[190:193], off
	v_cvt_pk_bf16_f32 v194, v28, v29
	v_cvt_pk_bf16_f32 v195, v30, v31
	v_cvt_pk_bf16_f32 v196, v24, v25
	v_cvt_pk_bf16_f32 v197, v26, v27
	global_store_dwordx4 v[156:157], v[194:197], off offset:256
	s_cmp_eq_u32 s12, 0
	s_cbranch_scc1 .Lp10_epi_done
	v_mov_b32_e32 v158, 0x10000
	v_mov_b32_e32 v159, 0
	v_lshl_add_u64 v[158:159], v[150:151], 0, v[158:159]
	v_cvt_pk_bf16_f32 v198, v100, v101
	v_cvt_pk_bf16_f32 v199, v102, v103
	v_cvt_pk_bf16_f32 v200, v96, v97
	v_cvt_pk_bf16_f32 v201, v98, v99
	global_store_dwordx4 v[158:159], v[198:201], off
	v_cvt_pk_bf16_f32 v202, v76, v77
	v_cvt_pk_bf16_f32 v203, v78, v79
	v_cvt_pk_bf16_f32 v204, v72, v73
	v_cvt_pk_bf16_f32 v205, v74, v75
	global_store_dwordx4 v[158:159], v[202:205], off offset:256
	v_mov_b32_e32 v160, 0x38000
	v_mov_b32_e32 v161, 0
	v_lshl_add_u64 v[160:161], v[150:151], 0, v[160:161]
	v_cvt_pk_bf16_f32 v206, v36, v37
	v_cvt_pk_bf16_f32 v207, v38, v39
	v_cvt_pk_bf16_f32 v208, v32, v33
	v_cvt_pk_bf16_f32 v209, v34, v35
	global_store_dwordx4 v[160:161], v[206:209], off
	v_cvt_pk_bf16_f32 v210, v12, v13
	v_cvt_pk_bf16_f32 v211, v14, v15
	v_cvt_pk_bf16_f32 v212, v8, v9
	v_cvt_pk_bf16_f32 v213, v10, v11
	global_store_dwordx4 v[160:161], v[210:213], off offset:256
.Lp10_epi_done:
	s_and_b64 vcc, exec, s[4:5]
	s_mov_b64 s[4:5], -1
	s_cbranch_vccnz .LBB0_1050
	s_andn2_b64 vcc, exec, s[8:9]
	s_cbranch_vccnz .LBB0_1049
	s_barrier
	s_branch .LBB0_1049

	.amdhsa_kernel _Z6fwd_mk4Args
		.amdhsa_group_segment_fixed_size 0
		.amdhsa_private_segment_fixed_size 0
		.amdhsa_kernarg_size 440
		.amdhsa_user_sgpr_count 2
		.amdhsa_user_sgpr_dispatch_ptr 0
		.amdhsa_user_sgpr_queue_ptr 0
		.amdhsa_user_sgpr_kernarg_segment_ptr 1
		.amdhsa_user_sgpr_dispatch_id 0
		.amdhsa_user_sgpr_kernarg_preload_length 0
		.amdhsa_user_sgpr_kernarg_preload_offset 0
		.amdhsa_user_sgpr_private_segment_size 0
		.amdhsa_uses_dynamic_stack 0
		.amdhsa_enable_private_segment 0
		.amdhsa_system_sgpr_workgroup_id_x 1
		.amdhsa_system_sgpr_workgroup_id_y 0
		.amdhsa_system_sgpr_workgroup_id_z 0
		.amdhsa_system_sgpr_workgroup_info 0
		.amdhsa_system_vgpr_workitem_id 0
		.amdhsa_next_free_vgpr 245
		.amdhsa_next_free_sgpr 102
		.amdhsa_accum_offset 248
		.amdhsa_reserve_vcc 1
		.amdhsa_float_round_mode_32 0
		.amdhsa_float_round_mode_16_64 0
		.amdhsa_float_denorm_mode_32 3
		.amdhsa_float_denorm_mode_16_64 3
		.amdhsa_dx10_clamp 1
		.amdhsa_ieee_mode 1
		.amdhsa_fp16_overflow 0
		.amdhsa_tg_split 0
		.amdhsa_exception_fp_ieee_invalid_op 0
		.amdhsa_exception_fp_denorm_src 0
		.amdhsa_exception_fp_ieee_div_zero 0
		.amdhsa_exception_fp_ieee_overflow 0
		.amdhsa_exception_fp_ieee_underflow 0
		.amdhsa_exception_fp_ieee_inexact 0
		.amdhsa_exception_int_div_zero 0
	.end_amdhsa_kernel

amdhsa.kernels:
  - .agpr_count:     0
    .args:
      - .offset:         0
        .size:           184
        .value_kind:     by_value
      - .offset:         184
        .size:           4
        .value_kind:     hidden_block_count_x
      - .offset:         188
        .size:           4
        .value_kind:     hidden_block_count_y
      - .offset:         192
        .size:           4
        .value_kind:     hidden_block_count_z
      - .offset:         196
        .size:           2
        .value_kind:     hidden_group_size_x
      - .offset:         198
        .size:           2
        .value_kind:     hidden_group_size_y
      - .offset:         200
        .size:           2
        .value_kind:     hidden_group_size_z
      - .offset:         202
        .size:           2
        .value_kind:     hidden_remainder_x
      - .offset:         204
        .size:           2
        .value_kind:     hidden_remainder_y
      - .offset:         206
        .size:           2
        .value_kind:     hidden_remainder_z
      - .offset:         224
        .size:           8
        .value_kind:     hidden_global_offset_x
      - .offset:         232
        .size:           8
        .value_kind:     hidden_global_offset_y
      - .offset:         240
        .size:           8
        .value_kind:     hidden_global_offset_z
      - .offset:         248
        .size:           2
        .value_kind:     hidden_grid_dims
      - .offset:         304
        .size:           4
        .value_kind:     hidden_dynamic_lds_size
    .group_segment_fixed_size: 0
    .kernarg_segment_align: 8
    .kernarg_segment_size: 440
    .language:       OpenCL C
    .language_version:
      - 2
      - 0
    .max_flat_workgroup_size: 512
    .name:           _Z6fwd_mk4Args
    .private_segment_fixed_size: 0
    .sgpr_count:     108
    .sgpr_spill_count: 10
    .symbol:         _Z6fwd_mk4Args.kd
    .uniform_work_group_size: 1
    .uses_dynamic_stack: false
    .vgpr_count:     245
    .vgpr_spill_count: 0
    .wavefront_size: 64
